# SwiGLU epilogue re-scheduled as a software pipeline over the 32 value pairs: transcendental ops alternate with the packed multiplies/adds of neighbouring pairs
# baseline (speedup 1.0000x reference)
; __device__ __forceinline__ v4u pk8(f32x4 a, f32x4 b) { v4u w; w.x = pk2(a[0], a[1]); w.y = pk2(a[2], a[3]); w.z = pk2(b[0], b[1]); w.w = pk2(b[2], b[3]); return w; }
;     __device__ __forceinline__ void operator()(const accv (&acc)[2][2][4][2], const pg8::Unit& u, int wr, int wc, int fr, int fq) const {
;         const int row0 = u.pm * 256 + wr * 64 + fr, col0 = u.pn * 128 + wc * 32 + 8 * fq;
; #pragma unroll
;         for (int ai = 0; ai < 2; ++ai)
; #pragma unroll
;             for (int m = 0; m < 4; ++m) {
;                 f32x4 a[2];
; #pragma unroll
;                 for (int n = 0; n < 2; ++n)
; #pragma unroll
;                     for (int i = 0; i < 4; ++i) { const float g = acc[ai][0][m][n][i], up = acc[ai][1][m][n][i];
;                         a[n][i] = g * __builtin_amdgcn_rcpf(1.f + __builtin_amdgcn_exp2f(-1.4426950408889634f * g)) * up; }
;                 *(v4u*)(O + (unsigned)((row0 + ai * 128 + m * 16) * FF + col0)) = pk8(a[0], a[1]);
;             }
;     }
.LBB0_233:
	v_lshl_add_u32 v147, s78, 8, v140
	v_lshl_or_b32 v146, s14, 7, v142
	s_movk_i32 s12, 0x1600
	s_andn2_b64 vcc, exec, s[4:5]
	s_mov_b64 s[4:5], -1
	s_mov_b32 s100, 0xbfb8aa3b
	s_mov_b32 s101, 0xbfb8aa3b
	v_mad_u64_u32 v[152:153], s[14:15], v147, s12, v[146:147]
	v_pk_mul_f32 v[156:157], v[124:125], s[100:101] op_sel_hi:[1,0]
	v_exp_f32_e32 v156, v156
	v_pk_mul_f32 v[158:159], v[126:127], s[100:101] op_sel_hi:[1,0]
	v_exp_f32_e32 v157, v157
	v_exp_f32_e32 v158, v158
	v_pk_mul_f32 v[160:161], v[120:121], s[100:101] op_sel_hi:[1,0]
	v_exp_f32_e32 v159, v159
	v_pk_add_f32 v[156:157], v[156:157], 1.0 op_sel_hi:[1,0]
	v_exp_f32_e32 v160, v160
	v_pk_mul_f32 v[162:163], v[122:123], s[100:101] op_sel_hi:[1,0]
	v_exp_f32_e32 v161, v161
	v_pk_add_f32 v[158:159], v[158:159], 1.0 op_sel_hi:[1,0]
	v_rcp_f32_e32 v156, v156
	v_rcp_f32_e32 v157, v157
	v_exp_f32_e32 v162, v162
	v_pk_mul_f32 v[164:165], v[108:109], s[100:101] op_sel_hi:[1,0]
	v_exp_f32_e32 v163, v163
	v_pk_add_f32 v[160:161], v[160:161], 1.0 op_sel_hi:[1,0]
	v_rcp_f32_e32 v158, v158
	v_pk_mul_f32 v[124:125], v[124:125], v[156:157]
	v_rcp_f32_e32 v159, v159
	v_exp_f32_e32 v164, v164
	v_pk_mul_f32 v[166:167], v[110:111], s[100:101] op_sel_hi:[1,0]
	v_exp_f32_e32 v165, v165
	v_pk_add_f32 v[162:163], v[162:163], 1.0 op_sel_hi:[1,0]
	v_rcp_f32_e32 v160, v160
	v_pk_mul_f32 v[126:127], v[126:127], v[158:159]
	v_rcp_f32_e32 v161, v161
	v_pk_mul_f32 v[124:125], v[124:125], v[116:117]
	v_exp_f32_e32 v166, v166
	v_pk_mul_f32 v[156:157], v[104:105], s[100:101] op_sel_hi:[1,0]
	v_exp_f32_e32 v167, v167
	v_pk_add_f32 v[164:165], v[164:165], 1.0 op_sel_hi:[1,0]
	v_rcp_f32_e32 v162, v162
	v_pk_mul_f32 v[120:121], v[120:121], v[160:161]
	v_rcp_f32_e32 v163, v163
	v_pk_mul_f32 v[126:127], v[126:127], v[118:119]
	v_cvt_pk_bf16_f32 v178, v124, v125
	v_mov_b32_e32 v168, v152
	v_exp_f32_e32 v156, v156
	v_pk_mul_f32 v[158:159], v[106:107], s[100:101] op_sel_hi:[1,0]
	v_exp_f32_e32 v157, v157
	v_pk_add_f32 v[166:167], v[166:167], 1.0 op_sel_hi:[1,0]
	v_rcp_f32_e32 v164, v164
	v_pk_mul_f32 v[122:123], v[122:123], v[162:163]
	v_rcp_f32_e32 v165, v165
	v_pk_mul_f32 v[120:121], v[120:121], v[112:113]
	v_cvt_pk_bf16_f32 v179, v126, v127
	v_exp_f32_e32 v158, v158
	v_pk_mul_f32 v[160:161], v[92:93], s[100:101] op_sel_hi:[1,0]
	v_exp_f32_e32 v159, v159
	v_pk_add_f32 v[156:157], v[156:157], 1.0 op_sel_hi:[1,0]
	v_rcp_f32_e32 v166, v166
	v_pk_mul_f32 v[108:109], v[108:109], v[164:165]
	v_rcp_f32_e32 v167, v167
	v_pk_mul_f32 v[122:123], v[122:123], v[114:115]
	v_cvt_pk_bf16_f32 v180, v120, v121
	v_lshl_add_u64 v[154:155], v[168:169], 1, s[64:65]
	v_exp_f32_e32 v160, v160
	v_pk_mul_f32 v[162:163], v[94:95], s[100:101] op_sel_hi:[1,0]
	v_exp_f32_e32 v161, v161
	v_pk_add_f32 v[158:159], v[158:159], 1.0 op_sel_hi:[1,0]
	v_rcp_f32_e32 v156, v156
	v_pk_mul_f32 v[110:111], v[110:111], v[166:167]
	v_rcp_f32_e32 v157, v157
	v_pk_mul_f32 v[108:109], v[108:109], v[100:101]
	v_cvt_pk_bf16_f32 v181, v122, v123
	global_store_dwordx4 v[154:155], v[178:181], off
	v_exp_f32_e32 v162, v162
	v_pk_mul_f32 v[164:165], v[88:89], s[100:101] op_sel_hi:[1,0]
	v_exp_f32_e32 v163, v163
	v_pk_add_f32 v[160:161], v[160:161], 1.0 op_sel_hi:[1,0]
	v_rcp_f32_e32 v158, v158
	v_pk_mul_f32 v[104:105], v[104:105], v[156:157]
	v_rcp_f32_e32 v159, v159
	v_pk_mul_f32 v[110:111], v[110:111], v[102:103]
	v_cvt_pk_bf16_f32 v182, v108, v109
	v_add_u32_e32 v168, 0x16000, v152
	v_exp_f32_e32 v164, v164
	v_pk_mul_f32 v[166:167], v[90:91], s[100:101] op_sel_hi:[1,0]
	v_exp_f32_e32 v165, v165
	v_pk_add_f32 v[162:163], v[162:163], 1.0 op_sel_hi:[1,0]
	v_rcp_f32_e32 v160, v160
	v_pk_mul_f32 v[106:107], v[106:107], v[158:159]
	v_rcp_f32_e32 v161, v161
	v_pk_mul_f32 v[104:105], v[104:105], v[96:97]
	v_cvt_pk_bf16_f32 v183, v110, v111
	v_exp_f32_e32 v166, v166
	v_pk_mul_f32 v[156:157], v[76:77], s[100:101] op_sel_hi:[1,0]
	v_exp_f32_e32 v167, v167
	v_pk_add_f32 v[164:165], v[164:165], 1.0 op_sel_hi:[1,0]
	v_rcp_f32_e32 v162, v162
	v_pk_mul_f32 v[92:93], v[92:93], v[160:161]
	v_rcp_f32_e32 v163, v163
	v_pk_mul_f32 v[106:107], v[106:107], v[98:99]
	v_cvt_pk_bf16_f32 v184, v104, v105
	v_lshl_add_u64 v[154:155], v[168:169], 1, s[64:65]
	v_exp_f32_e32 v156, v156
	v_pk_mul_f32 v[158:159], v[78:79], s[100:101] op_sel_hi:[1,0]
	v_exp_f32_e32 v157, v157
	v_pk_add_f32 v[166:167], v[166:167], 1.0 op_sel_hi:[1,0]
	v_rcp_f32_e32 v164, v164
	v_pk_mul_f32 v[94:95], v[94:95], v[162:163]
	v_rcp_f32_e32 v165, v165
	v_pk_mul_f32 v[92:93], v[92:93], v[84:85]
	v_cvt_pk_bf16_f32 v185, v106, v107
	global_store_dwordx4 v[154:155], v[182:185], off
	v_exp_f32_e32 v158, v158
	v_pk_mul_f32 v[160:161], v[72:73], s[100:101] op_sel_hi:[1,0]
	v_exp_f32_e32 v159, v159
	v_pk_add_f32 v[156:157], v[156:157], 1.0 op_sel_hi:[1,0]
	v_rcp_f32_e32 v166, v166
	v_pk_mul_f32 v[88:89], v[88:89], v[164:165]
	v_rcp_f32_e32 v167, v167
	v_pk_mul_f32 v[94:95], v[94:95], v[86:87]
	v_cvt_pk_bf16_f32 v178, v92, v93
	v_add_u32_e32 v168, 0x2c000, v152
	v_exp_f32_e32 v160, v160
	v_pk_mul_f32 v[162:163], v[74:75], s[100:101] op_sel_hi:[1,0]
	v_exp_f32_e32 v161, v161
	v_pk_add_f32 v[158:159], v[158:159], 1.0 op_sel_hi:[1,0]
	v_rcp_f32_e32 v156, v156
	v_pk_mul_f32 v[90:91], v[90:91], v[166:167]
	v_rcp_f32_e32 v157, v157
	v_pk_mul_f32 v[88:89], v[88:89], v[80:81]
	v_cvt_pk_bf16_f32 v179, v94, v95
	v_exp_f32_e32 v162, v162
	v_pk_mul_f32 v[164:165], v[60:61], s[100:101] op_sel_hi:[1,0]
	v_exp_f32_e32 v163, v163
	v_pk_add_f32 v[160:161], v[160:161], 1.0 op_sel_hi:[1,0]
	v_rcp_f32_e32 v158, v158
	v_pk_mul_f32 v[76:77], v[76:77], v[156:157]
	v_rcp_f32_e32 v159, v159
	v_pk_mul_f32 v[90:91], v[90:91], v[82:83]
	v_cvt_pk_bf16_f32 v180, v88, v89
; __device__ __forceinline__ v4u pk8(f32x4 a, f32x4 b) { v4u w; w.x = pk2(a[0], a[1]); w.y = pk2(a[2], a[3]); w.z = pk2(b[0], b[1]); w.w = pk2(b[2], b[3]); return w; }
;     __device__ __forceinline__ void operator()(const accv (&acc)[2][2][4][2], const pg8::Unit& u, int wr, int wc, int fr, int fq) const {
;         const int row0 = u.pm * 256 + wr * 64 + fr, col0 = u.pn * 128 + wc * 32 + 8 * fq;
; #pragma unroll
;         for (int ai = 0; ai < 2; ++ai)
; #pragma unroll
;             for (int m = 0; m < 4; ++m) {
;                 f32x4 a[2];
; #pragma unroll
;                 for (int n = 0; n < 2; ++n)
; #pragma unroll
;                     for (int i = 0; i < 4; ++i) { const float g = acc[ai][0][m][n][i], up = acc[ai][1][m][n][i];
;                         a[n][i] = g * __builtin_amdgcn_rcpf(1.f + __builtin_amdgcn_exp2f(-1.4426950408889634f * g)) * up; }
;                 *(v4u*)(O + (unsigned)((row0 + ai * 128 + m * 16) * FF + col0)) = pk8(a[0], a[1]);
;             }
;     }
	v_lshl_add_u64 v[154:155], v[168:169], 1, s[64:65]
	v_exp_f32_e32 v164, v164
	v_pk_mul_f32 v[166:167], v[62:63], s[100:101] op_sel_hi:[1,0]
	v_exp_f32_e32 v165, v165
	v_pk_add_f32 v[162:163], v[162:163], 1.0 op_sel_hi:[1,0]
	v_rcp_f32_e32 v160, v160
	v_pk_mul_f32 v[78:79], v[78:79], v[158:159]
	v_rcp_f32_e32 v161, v161
	v_pk_mul_f32 v[76:77], v[76:77], v[68:69]
	v_cvt_pk_bf16_f32 v181, v90, v91
	global_store_dwordx4 v[154:155], v[178:181], off
	v_exp_f32_e32 v166, v166
	v_pk_mul_f32 v[156:157], v[56:57], s[100:101] op_sel_hi:[1,0]
	v_exp_f32_e32 v167, v167
	v_pk_add_f32 v[164:165], v[164:165], 1.0 op_sel_hi:[1,0]
	v_rcp_f32_e32 v162, v162
	v_pk_mul_f32 v[72:73], v[72:73], v[160:161]
	v_rcp_f32_e32 v163, v163
	v_pk_mul_f32 v[78:79], v[78:79], v[70:71]
	v_cvt_pk_bf16_f32 v182, v76, v77
	v_add_u32_e32 v168, 0x42000, v152
	v_exp_f32_e32 v156, v156
	v_pk_mul_f32 v[158:159], v[58:59], s[100:101] op_sel_hi:[1,0]
	v_exp_f32_e32 v157, v157
	v_pk_add_f32 v[166:167], v[166:167], 1.0 op_sel_hi:[1,0]
	v_rcp_f32_e32 v164, v164
	v_pk_mul_f32 v[74:75], v[74:75], v[162:163]
	v_rcp_f32_e32 v165, v165
	v_pk_mul_f32 v[72:73], v[72:73], v[64:65]
	v_cvt_pk_bf16_f32 v183, v78, v79
	v_exp_f32_e32 v158, v158
	v_pk_mul_f32 v[160:161], v[44:45], s[100:101] op_sel_hi:[1,0]
	v_exp_f32_e32 v159, v159
	v_pk_add_f32 v[156:157], v[156:157], 1.0 op_sel_hi:[1,0]
	v_rcp_f32_e32 v166, v166
	v_pk_mul_f32 v[60:61], v[60:61], v[164:165]
	v_rcp_f32_e32 v167, v167
	v_pk_mul_f32 v[74:75], v[74:75], v[66:67]
	v_cvt_pk_bf16_f32 v184, v72, v73
	v_lshl_add_u64 v[154:155], v[168:169], 1, s[64:65]
	v_exp_f32_e32 v160, v160
	v_pk_mul_f32 v[162:163], v[46:47], s[100:101] op_sel_hi:[1,0]
	v_exp_f32_e32 v161, v161
	v_pk_add_f32 v[158:159], v[158:159], 1.0 op_sel_hi:[1,0]
	v_rcp_f32_e32 v156, v156
	v_pk_mul_f32 v[62:63], v[62:63], v[166:167]
	v_rcp_f32_e32 v157, v157
	v_pk_mul_f32 v[60:61], v[60:61], v[52:53]
	v_cvt_pk_bf16_f32 v185, v74, v75
	global_store_dwordx4 v[154:155], v[182:185], off
	v_exp_f32_e32 v162, v162
	v_pk_mul_f32 v[164:165], v[40:41], s[100:101] op_sel_hi:[1,0]
	v_exp_f32_e32 v163, v163
	v_pk_add_f32 v[160:161], v[160:161], 1.0 op_sel_hi:[1,0]
	v_rcp_f32_e32 v158, v158
	v_pk_mul_f32 v[56:57], v[56:57], v[156:157]
	v_rcp_f32_e32 v159, v159
	v_pk_mul_f32 v[62:63], v[62:63], v[54:55]
	v_cvt_pk_bf16_f32 v178, v60, v61
	v_add_u32_e32 v168, 0xb0000, v152
	v_exp_f32_e32 v164, v164
	v_pk_mul_f32 v[166:167], v[42:43], s[100:101] op_sel_hi:[1,0]
	v_exp_f32_e32 v165, v165
	v_pk_add_f32 v[162:163], v[162:163], 1.0 op_sel_hi:[1,0]
	v_rcp_f32_e32 v160, v160
	v_pk_mul_f32 v[58:59], v[58:59], v[158:159]
	v_rcp_f32_e32 v161, v161
	v_pk_mul_f32 v[56:57], v[56:57], v[48:49]
	v_cvt_pk_bf16_f32 v179, v62, v63
	v_exp_f32_e32 v166, v166
	v_pk_mul_f32 v[156:157], v[28:29], s[100:101] op_sel_hi:[1,0]
	v_exp_f32_e32 v167, v167
	v_pk_add_f32 v[164:165], v[164:165], 1.0 op_sel_hi:[1,0]
	v_rcp_f32_e32 v162, v162
	v_pk_mul_f32 v[44:45], v[44:45], v[160:161]
	v_rcp_f32_e32 v163, v163
	v_pk_mul_f32 v[58:59], v[58:59], v[50:51]
	v_cvt_pk_bf16_f32 v180, v56, v57
	v_lshl_add_u64 v[154:155], v[168:169], 1, s[64:65]
	v_exp_f32_e32 v156, v156
	v_pk_mul_f32 v[158:159], v[30:31], s[100:101] op_sel_hi:[1,0]
	v_exp_f32_e32 v157, v157
	v_pk_add_f32 v[166:167], v[166:167], 1.0 op_sel_hi:[1,0]
	v_rcp_f32_e32 v164, v164
	v_pk_mul_f32 v[46:47], v[46:47], v[162:163]
	v_rcp_f32_e32 v165, v165
	v_pk_mul_f32 v[44:45], v[44:45], v[36:37]
	v_cvt_pk_bf16_f32 v181, v58, v59
	global_store_dwordx4 v[154:155], v[178:181], off
	v_exp_f32_e32 v158, v158
	v_pk_mul_f32 v[160:161], v[24:25], s[100:101] op_sel_hi:[1,0]
	v_exp_f32_e32 v159, v159
	v_pk_add_f32 v[156:157], v[156:157], 1.0 op_sel_hi:[1,0]
	v_rcp_f32_e32 v166, v166
	v_pk_mul_f32 v[40:41], v[40:41], v[164:165]
	v_rcp_f32_e32 v167, v167
	v_pk_mul_f32 v[46:47], v[46:47], v[38:39]
	v_cvt_pk_bf16_f32 v182, v44, v45
	v_add_u32_e32 v168, 0xc6000, v152
	v_exp_f32_e32 v160, v160
	v_pk_mul_f32 v[162:163], v[26:27], s[100:101] op_sel_hi:[1,0]
	v_exp_f32_e32 v161, v161
	v_pk_add_f32 v[158:159], v[158:159], 1.0 op_sel_hi:[1,0]
	v_rcp_f32_e32 v156, v156
	v_pk_mul_f32 v[42:43], v[42:43], v[166:167]
	v_rcp_f32_e32 v157, v157
	v_pk_mul_f32 v[40:41], v[40:41], v[32:33]
	v_cvt_pk_bf16_f32 v183, v46, v47
	v_exp_f32_e32 v162, v162
	v_pk_mul_f32 v[164:165], v[12:13], s[100:101] op_sel_hi:[1,0]
	v_exp_f32_e32 v163, v163
	v_pk_add_f32 v[160:161], v[160:161], 1.0 op_sel_hi:[1,0]
	v_rcp_f32_e32 v158, v158
	v_pk_mul_f32 v[28:29], v[28:29], v[156:157]
	v_rcp_f32_e32 v159, v159
	v_pk_mul_f32 v[42:43], v[42:43], v[34:35]
	v_cvt_pk_bf16_f32 v184, v40, v41
	v_lshl_add_u64 v[154:155], v[168:169], 1, s[64:65]
	v_exp_f32_e32 v164, v164
	v_pk_mul_f32 v[166:167], v[14:15], s[100:101] op_sel_hi:[1,0]
	v_exp_f32_e32 v165, v165
	v_pk_add_f32 v[162:163], v[162:163], 1.0 op_sel_hi:[1,0]
	v_rcp_f32_e32 v160, v160
	v_pk_mul_f32 v[30:31], v[30:31], v[158:159]
	v_rcp_f32_e32 v161, v161
	v_pk_mul_f32 v[28:29], v[28:29], v[20:21]
	v_cvt_pk_bf16_f32 v185, v42, v43
	global_store_dwordx4 v[154:155], v[182:185], off
	v_exp_f32_e32 v166, v166
	v_pk_mul_f32 v[156:157], v[8:9], s[100:101] op_sel_hi:[1,0]
	v_exp_f32_e32 v167, v167
	v_pk_add_f32 v[164:165], v[164:165], 1.0 op_sel_hi:[1,0]
	v_rcp_f32_e32 v162, v162
	v_pk_mul_f32 v[24:25], v[24:25], v[160:161]
	v_rcp_f32_e32 v163, v163
	v_pk_mul_f32 v[30:31], v[30:31], v[22:23]
	v_cvt_pk_bf16_f32 v178, v28, v29
	v_add_u32_e32 v168, 0xdc000, v152
	v_exp_f32_e32 v156, v156
	v_pk_mul_f32 v[158:159], v[10:11], s[100:101] op_sel_hi:[1,0]
	v_exp_f32_e32 v157, v157
	v_pk_add_f32 v[166:167], v[166:167], 1.0 op_sel_hi:[1,0]
	v_rcp_f32_e32 v164, v164
	v_pk_mul_f32 v[26:27], v[26:27], v[162:163]
	v_rcp_f32_e32 v165, v165
	v_pk_mul_f32 v[24:25], v[24:25], v[16:17]
	v_cvt_pk_bf16_f32 v179, v30, v31
	v_exp_f32_e32 v158, v158
	v_pk_add_f32 v[156:157], v[156:157], 1.0 op_sel_hi:[1,0]
	v_exp_f32_e32 v159, v159
	v_pk_mul_f32 v[12:13], v[12:13], v[164:165]
	v_rcp_f32_e32 v166, v166
	v_pk_mul_f32 v[26:27], v[26:27], v[18:19]
	v_rcp_f32_e32 v167, v167
	v_cvt_pk_bf16_f32 v180, v24, v25
	v_lshl_add_u64 v[154:155], v[168:169], 1, s[64:65]
	v_rcp_f32_e32 v156, v156
	v_pk_add_f32 v[158:159], v[158:159], 1.0 op_sel_hi:[1,0]
	v_rcp_f32_e32 v157, v157
	v_pk_mul_f32 v[14:15], v[14:15], v[166:167]
	v_pk_mul_f32 v[12:13], v[12:13], v[4:5]
	v_cvt_pk_bf16_f32 v181, v26, v27
	global_store_dwordx4 v[154:155], v[178:181], off
	v_rcp_f32_e32 v158, v158
	v_pk_mul_f32 v[8:9], v[8:9], v[156:157]
	v_rcp_f32_e32 v159, v159
	v_pk_mul_f32 v[14:15], v[14:15], v[6:7]
	v_cvt_pk_bf16_f32 v182, v12, v13
	v_add_u32_e32 v168, 0xf2000, v152
	v_pk_mul_f32 v[10:11], v[10:11], v[158:159]
	v_pk_mul_f32 v[8:9], v[8:9], v[0:1]
	v_cvt_pk_bf16_f32 v183, v14, v15
	v_pk_mul_f32 v[10:11], v[10:11], v[2:3]
	v_cvt_pk_bf16_f32 v184, v8, v9
	v_lshl_add_u64 v[154:155], v[168:169], 1, s[64:65]
	v_cvt_pk_bf16_f32 v185, v10, v11
	global_store_dwordx4 v[154:155], v[182:185], off
	s_cbranch_vccnz .LBB0_226
	s_andn2_b64 vcc, exec, s[6:7]
	s_cbranch_vccnz .LBB0_225
	s_barrier
	s_branch .LBB0_225

; __device__ __forceinline__ v4u pk8(f32x4 a, f32x4 b) { v4u w; w.x = pk2(a[0], a[1]); w.y = pk2(a[2], a[3]); w.z = pk2(b[0], b[1]); w.w = pk2(b[2], b[3]); return w; }
;     __device__ __forceinline__ void operator()(const accv (&acc)[2][2][4][2], const pg8::Unit& u, int wr, int wc, int fr, int fq) const {
;         const int row0 = u.pm * 256 + wr * 64 + fr, col0 = u.pn * 128 + wc * 32 + 8 * fq;
; #pragma unroll
;         for (int ai = 0; ai < 2; ++ai)
; #pragma unroll
;             for (int m = 0; m < 4; ++m) {
;                 f32x4 a[2];
; #pragma unroll
;                 for (int n = 0; n < 2; ++n)
; #pragma unroll
;                     for (int i = 0; i < 4; ++i) { const float g = acc[ai][0][m][n][i], up = acc[ai][1][m][n][i];
;                         a[n][i] = g * __builtin_amdgcn_rcpf(1.f + __builtin_amdgcn_exp2f(-1.4426950408889634f * g)) * up; }
;                 *(v4u*)(O + (unsigned)((row0 + ai * 128 + m * 16) * FF + col0)) = pk8(a[0], a[1]);
;             }
;     }
.LBB0_986:
	v_lshl_add_u32 v147, s68, 8, v140
	v_lshl_or_b32 v146, s14, 7, v142
	s_movk_i32 s2, 0x1600
	s_andn2_b64 vcc, exec, s[0:1]
	s_mov_b64 s[0:1], -1
	s_mov_b32 s100, 0xbfb8aa3b
	s_mov_b32 s101, 0xbfb8aa3b
	v_mad_u64_u32 v[152:153], s[2:3], v147, s2, v[146:147]
	v_pk_mul_f32 v[156:157], v[124:125], s[100:101] op_sel_hi:[1,0]
	v_exp_f32_e32 v156, v156
	v_pk_mul_f32 v[158:159], v[126:127], s[100:101] op_sel_hi:[1,0]
	v_exp_f32_e32 v157, v157
	v_exp_f32_e32 v158, v158
	v_pk_mul_f32 v[160:161], v[120:121], s[100:101] op_sel_hi:[1,0]
	v_exp_f32_e32 v159, v159
	v_pk_add_f32 v[156:157], v[156:157], 1.0 op_sel_hi:[1,0]
	v_exp_f32_e32 v160, v160
	v_pk_mul_f32 v[162:163], v[122:123], s[100:101] op_sel_hi:[1,0]
	v_exp_f32_e32 v161, v161
	v_pk_add_f32 v[158:159], v[158:159], 1.0 op_sel_hi:[1,0]
	v_rcp_f32_e32 v156, v156
	v_rcp_f32_e32 v157, v157
	v_exp_f32_e32 v162, v162
	v_pk_mul_f32 v[164:165], v[108:109], s[100:101] op_sel_hi:[1,0]
	v_exp_f32_e32 v163, v163
	v_pk_add_f32 v[160:161], v[160:161], 1.0 op_sel_hi:[1,0]
	v_rcp_f32_e32 v158, v158
	v_pk_mul_f32 v[124:125], v[124:125], v[156:157]
	v_rcp_f32_e32 v159, v159
	v_exp_f32_e32 v164, v164
	v_pk_mul_f32 v[166:167], v[110:111], s[100:101] op_sel_hi:[1,0]
	v_exp_f32_e32 v165, v165
	v_pk_add_f32 v[162:163], v[162:163], 1.0 op_sel_hi:[1,0]
	v_rcp_f32_e32 v160, v160
	v_pk_mul_f32 v[126:127], v[126:127], v[158:159]
	v_rcp_f32_e32 v161, v161
	v_pk_mul_f32 v[124:125], v[124:125], v[116:117]
	v_exp_f32_e32 v166, v166
	v_pk_mul_f32 v[156:157], v[104:105], s[100:101] op_sel_hi:[1,0]
	v_exp_f32_e32 v167, v167
	v_pk_add_f32 v[164:165], v[164:165], 1.0 op_sel_hi:[1,0]
	v_rcp_f32_e32 v162, v162
	v_pk_mul_f32 v[120:121], v[120:121], v[160:161]
	v_rcp_f32_e32 v163, v163
	v_pk_mul_f32 v[126:127], v[126:127], v[118:119]
	v_cvt_pk_bf16_f32 v178, v124, v125
	v_mov_b32_e32 v168, v152
	v_exp_f32_e32 v156, v156
	v_pk_mul_f32 v[158:159], v[106:107], s[100:101] op_sel_hi:[1,0]
	v_exp_f32_e32 v157, v157
	v_pk_add_f32 v[166:167], v[166:167], 1.0 op_sel_hi:[1,0]
	v_rcp_f32_e32 v164, v164
	v_pk_mul_f32 v[122:123], v[122:123], v[162:163]
	v_rcp_f32_e32 v165, v165
	v_pk_mul_f32 v[120:121], v[120:121], v[112:113]
	v_cvt_pk_bf16_f32 v179, v126, v127
	v_exp_f32_e32 v158, v158
	v_pk_mul_f32 v[160:161], v[92:93], s[100:101] op_sel_hi:[1,0]
	v_exp_f32_e32 v159, v159
	v_pk_add_f32 v[156:157], v[156:157], 1.0 op_sel_hi:[1,0]
	v_rcp_f32_e32 v166, v166
	v_pk_mul_f32 v[108:109], v[108:109], v[164:165]
	v_rcp_f32_e32 v167, v167
	v_pk_mul_f32 v[122:123], v[122:123], v[114:115]
	v_cvt_pk_bf16_f32 v180, v120, v121
	v_lshl_add_u64 v[154:155], v[168:169], 1, s[64:65]
	v_exp_f32_e32 v160, v160
	v_pk_mul_f32 v[162:163], v[94:95], s[100:101] op_sel_hi:[1,0]
	v_exp_f32_e32 v161, v161
	v_pk_add_f32 v[158:159], v[158:159], 1.0 op_sel_hi:[1,0]
	v_rcp_f32_e32 v156, v156
	v_pk_mul_f32 v[110:111], v[110:111], v[166:167]
	v_rcp_f32_e32 v157, v157
	v_pk_mul_f32 v[108:109], v[108:109], v[100:101]
	v_cvt_pk_bf16_f32 v181, v122, v123
	global_store_dwordx4 v[154:155], v[178:181], off
	v_exp_f32_e32 v162, v162
	v_pk_mul_f32 v[164:165], v[88:89], s[100:101] op_sel_hi:[1,0]
	v_exp_f32_e32 v163, v163
	v_pk_add_f32 v[160:161], v[160:161], 1.0 op_sel_hi:[1,0]
	v_rcp_f32_e32 v158, v158
	v_pk_mul_f32 v[104:105], v[104:105], v[156:157]
	v_rcp_f32_e32 v159, v159
	v_pk_mul_f32 v[110:111], v[110:111], v[102:103]
	v_cvt_pk_bf16_f32 v182, v108, v109
	v_add_u32_e32 v168, 0x16000, v152
	v_exp_f32_e32 v164, v164
	v_pk_mul_f32 v[166:167], v[90:91], s[100:101] op_sel_hi:[1,0]
	v_exp_f32_e32 v165, v165
	v_pk_add_f32 v[162:163], v[162:163], 1.0 op_sel_hi:[1,0]
	v_rcp_f32_e32 v160, v160
	v_pk_mul_f32 v[106:107], v[106:107], v[158:159]
	v_rcp_f32_e32 v161, v161
	v_pk_mul_f32 v[104:105], v[104:105], v[96:97]
	v_cvt_pk_bf16_f32 v183, v110, v111
	v_exp_f32_e32 v166, v166
	v_pk_mul_f32 v[156:157], v[76:77], s[100:101] op_sel_hi:[1,0]
	v_exp_f32_e32 v167, v167
	v_pk_add_f32 v[164:165], v[164:165], 1.0 op_sel_hi:[1,0]
	v_rcp_f32_e32 v162, v162
	v_pk_mul_f32 v[92:93], v[92:93], v[160:161]
	v_rcp_f32_e32 v163, v163
	v_pk_mul_f32 v[106:107], v[106:107], v[98:99]
	v_cvt_pk_bf16_f32 v184, v104, v105
	v_lshl_add_u64 v[154:155], v[168:169], 1, s[64:65]
	v_exp_f32_e32 v156, v156
	v_pk_mul_f32 v[158:159], v[78:79], s[100:101] op_sel_hi:[1,0]
	v_exp_f32_e32 v157, v157
	v_pk_add_f32 v[166:167], v[166:167], 1.0 op_sel_hi:[1,0]
	v_rcp_f32_e32 v164, v164
	v_pk_mul_f32 v[94:95], v[94:95], v[162:163]
	v_rcp_f32_e32 v165, v165
	v_pk_mul_f32 v[92:93], v[92:93], v[84:85]
	v_cvt_pk_bf16_f32 v185, v106, v107
	global_store_dwordx4 v[154:155], v[182:185], off
	v_exp_f32_e32 v158, v158
	v_pk_mul_f32 v[160:161], v[72:73], s[100:101] op_sel_hi:[1,0]
	v_exp_f32_e32 v159, v159
	v_pk_add_f32 v[156:157], v[156:157], 1.0 op_sel_hi:[1,0]
	v_rcp_f32_e32 v166, v166
	v_pk_mul_f32 v[88:89], v[88:89], v[164:165]
	v_rcp_f32_e32 v167, v167
	v_pk_mul_f32 v[94:95], v[94:95], v[86:87]
	v_cvt_pk_bf16_f32 v178, v92, v93
	v_add_u32_e32 v168, 0x2c000, v152
	v_exp_f32_e32 v160, v160
	v_pk_mul_f32 v[162:163], v[74:75], s[100:101] op_sel_hi:[1,0]
	v_exp_f32_e32 v161, v161
	v_pk_add_f32 v[158:159], v[158:159], 1.0 op_sel_hi:[1,0]
	v_rcp_f32_e32 v156, v156
	v_pk_mul_f32 v[90:91], v[90:91], v[166:167]
	v_rcp_f32_e32 v157, v157
	v_pk_mul_f32 v[88:89], v[88:89], v[80:81]
	v_cvt_pk_bf16_f32 v179, v94, v95
	v_exp_f32_e32 v162, v162
	v_pk_mul_f32 v[164:165], v[60:61], s[100:101] op_sel_hi:[1,0]
	v_exp_f32_e32 v163, v163
	v_pk_add_f32 v[160:161], v[160:161], 1.0 op_sel_hi:[1,0]
	v_rcp_f32_e32 v158, v158
	v_pk_mul_f32 v[76:77], v[76:77], v[156:157]
	v_rcp_f32_e32 v159, v159
	v_pk_mul_f32 v[90:91], v[90:91], v[82:83]
	v_cvt_pk_bf16_f32 v180, v88, v89
; __device__ __forceinline__ v4u pk8(f32x4 a, f32x4 b) { v4u w; w.x = pk2(a[0], a[1]); w.y = pk2(a[2], a[3]); w.z = pk2(b[0], b[1]); w.w = pk2(b[2], b[3]); return w; }
;     __device__ __forceinline__ void operator()(const accv (&acc)[2][2][4][2], const pg8::Unit& u, int wr, int wc, int fr, int fq) const {
;         const int row0 = u.pm * 256 + wr * 64 + fr, col0 = u.pn * 128 + wc * 32 + 8 * fq;
; #pragma unroll
;         for (int ai = 0; ai < 2; ++ai)
; #pragma unroll
;             for (int m = 0; m < 4; ++m) {
;                 f32x4 a[2];
; #pragma unroll
;                 for (int n = 0; n < 2; ++n)
; #pragma unroll
;                     for (int i = 0; i < 4; ++i) { const float g = acc[ai][0][m][n][i], up = acc[ai][1][m][n][i];
;                         a[n][i] = g * __builtin_amdgcn_rcpf(1.f + __builtin_amdgcn_exp2f(-1.4426950408889634f * g)) * up; }
;                 *(v4u*)(O + (unsigned)((row0 + ai * 128 + m * 16) * FF + col0)) = pk8(a[0], a[1]);
;             }
;     }
	v_lshl_add_u64 v[154:155], v[168:169], 1, s[64:65]
	v_exp_f32_e32 v164, v164
	v_pk_mul_f32 v[166:167], v[62:63], s[100:101] op_sel_hi:[1,0]
	v_exp_f32_e32 v165, v165
	v_pk_add_f32 v[162:163], v[162:163], 1.0 op_sel_hi:[1,0]
	v_rcp_f32_e32 v160, v160
	v_pk_mul_f32 v[78:79], v[78:79], v[158:159]
	v_rcp_f32_e32 v161, v161
	v_pk_mul_f32 v[76:77], v[76:77], v[68:69]
	v_cvt_pk_bf16_f32 v181, v90, v91
	global_store_dwordx4 v[154:155], v[178:181], off
	v_exp_f32_e32 v166, v166
	v_pk_mul_f32 v[156:157], v[56:57], s[100:101] op_sel_hi:[1,0]
	v_exp_f32_e32 v167, v167
	v_pk_add_f32 v[164:165], v[164:165], 1.0 op_sel_hi:[1,0]
	v_rcp_f32_e32 v162, v162
	v_pk_mul_f32 v[72:73], v[72:73], v[160:161]
	v_rcp_f32_e32 v163, v163
	v_pk_mul_f32 v[78:79], v[78:79], v[70:71]
	v_cvt_pk_bf16_f32 v182, v76, v77
	v_add_u32_e32 v168, 0x42000, v152
	v_exp_f32_e32 v156, v156
	v_pk_mul_f32 v[158:159], v[58:59], s[100:101] op_sel_hi:[1,0]
	v_exp_f32_e32 v157, v157
	v_pk_add_f32 v[166:167], v[166:167], 1.0 op_sel_hi:[1,0]
	v_rcp_f32_e32 v164, v164
	v_pk_mul_f32 v[74:75], v[74:75], v[162:163]
	v_rcp_f32_e32 v165, v165
	v_pk_mul_f32 v[72:73], v[72:73], v[64:65]
	v_cvt_pk_bf16_f32 v183, v78, v79
	v_exp_f32_e32 v158, v158
	v_pk_mul_f32 v[160:161], v[44:45], s[100:101] op_sel_hi:[1,0]
	v_exp_f32_e32 v159, v159
	v_pk_add_f32 v[156:157], v[156:157], 1.0 op_sel_hi:[1,0]
	v_rcp_f32_e32 v166, v166
	v_pk_mul_f32 v[60:61], v[60:61], v[164:165]
	v_rcp_f32_e32 v167, v167
	v_pk_mul_f32 v[74:75], v[74:75], v[66:67]
	v_cvt_pk_bf16_f32 v184, v72, v73
	v_lshl_add_u64 v[154:155], v[168:169], 1, s[64:65]
	v_exp_f32_e32 v160, v160
	v_pk_mul_f32 v[162:163], v[46:47], s[100:101] op_sel_hi:[1,0]
	v_exp_f32_e32 v161, v161
	v_pk_add_f32 v[158:159], v[158:159], 1.0 op_sel_hi:[1,0]
	v_rcp_f32_e32 v156, v156
	v_pk_mul_f32 v[62:63], v[62:63], v[166:167]
	v_rcp_f32_e32 v157, v157
	v_pk_mul_f32 v[60:61], v[60:61], v[52:53]
	v_cvt_pk_bf16_f32 v185, v74, v75
	global_store_dwordx4 v[154:155], v[182:185], off
	v_exp_f32_e32 v162, v162
	v_pk_mul_f32 v[164:165], v[40:41], s[100:101] op_sel_hi:[1,0]
	v_exp_f32_e32 v163, v163
	v_pk_add_f32 v[160:161], v[160:161], 1.0 op_sel_hi:[1,0]
	v_rcp_f32_e32 v158, v158
	v_pk_mul_f32 v[56:57], v[56:57], v[156:157]
	v_rcp_f32_e32 v159, v159
	v_pk_mul_f32 v[62:63], v[62:63], v[54:55]
	v_cvt_pk_bf16_f32 v178, v60, v61
	v_add_u32_e32 v168, 0xb0000, v152
	v_exp_f32_e32 v164, v164
	v_pk_mul_f32 v[166:167], v[42:43], s[100:101] op_sel_hi:[1,0]
	v_exp_f32_e32 v165, v165
	v_pk_add_f32 v[162:163], v[162:163], 1.0 op_sel_hi:[1,0]
	v_rcp_f32_e32 v160, v160
	v_pk_mul_f32 v[58:59], v[58:59], v[158:159]
	v_rcp_f32_e32 v161, v161
	v_pk_mul_f32 v[56:57], v[56:57], v[48:49]
	v_cvt_pk_bf16_f32 v179, v62, v63
	v_exp_f32_e32 v166, v166
	v_pk_mul_f32 v[156:157], v[28:29], s[100:101] op_sel_hi:[1,0]
	v_exp_f32_e32 v167, v167
	v_pk_add_f32 v[164:165], v[164:165], 1.0 op_sel_hi:[1,0]
	v_rcp_f32_e32 v162, v162
	v_pk_mul_f32 v[44:45], v[44:45], v[160:161]
	v_rcp_f32_e32 v163, v163
	v_pk_mul_f32 v[58:59], v[58:59], v[50:51]
	v_cvt_pk_bf16_f32 v180, v56, v57
	v_lshl_add_u64 v[154:155], v[168:169], 1, s[64:65]
	v_exp_f32_e32 v156, v156
	v_pk_mul_f32 v[158:159], v[30:31], s[100:101] op_sel_hi:[1,0]
	v_exp_f32_e32 v157, v157
	v_pk_add_f32 v[166:167], v[166:167], 1.0 op_sel_hi:[1,0]
	v_rcp_f32_e32 v164, v164
	v_pk_mul_f32 v[46:47], v[46:47], v[162:163]
	v_rcp_f32_e32 v165, v165
	v_pk_mul_f32 v[44:45], v[44:45], v[36:37]
	v_cvt_pk_bf16_f32 v181, v58, v59
	global_store_dwordx4 v[154:155], v[178:181], off
	v_exp_f32_e32 v158, v158
	v_pk_mul_f32 v[160:161], v[24:25], s[100:101] op_sel_hi:[1,0]
	v_exp_f32_e32 v159, v159
	v_pk_add_f32 v[156:157], v[156:157], 1.0 op_sel_hi:[1,0]
	v_rcp_f32_e32 v166, v166
	v_pk_mul_f32 v[40:41], v[40:41], v[164:165]
	v_rcp_f32_e32 v167, v167
	v_pk_mul_f32 v[46:47], v[46:47], v[38:39]
	v_cvt_pk_bf16_f32 v182, v44, v45
	v_add_u32_e32 v168, 0xc6000, v152
	v_exp_f32_e32 v160, v160
	v_pk_mul_f32 v[162:163], v[26:27], s[100:101] op_sel_hi:[1,0]
	v_exp_f32_e32 v161, v161
	v_pk_add_f32 v[158:159], v[158:159], 1.0 op_sel_hi:[1,0]
	v_rcp_f32_e32 v156, v156
	v_pk_mul_f32 v[42:43], v[42:43], v[166:167]
	v_rcp_f32_e32 v157, v157
	v_pk_mul_f32 v[40:41], v[40:41], v[32:33]
	v_cvt_pk_bf16_f32 v183, v46, v47
	v_exp_f32_e32 v162, v162
	v_pk_mul_f32 v[164:165], v[12:13], s[100:101] op_sel_hi:[1,0]
	v_exp_f32_e32 v163, v163
	v_pk_add_f32 v[160:161], v[160:161], 1.0 op_sel_hi:[1,0]
	v_rcp_f32_e32 v158, v158
	v_pk_mul_f32 v[28:29], v[28:29], v[156:157]
	v_rcp_f32_e32 v159, v159
	v_pk_mul_f32 v[42:43], v[42:43], v[34:35]
	v_cvt_pk_bf16_f32 v184, v40, v41
	v_lshl_add_u64 v[154:155], v[168:169], 1, s[64:65]
	v_exp_f32_e32 v164, v164
	v_pk_mul_f32 v[166:167], v[14:15], s[100:101] op_sel_hi:[1,0]
	v_exp_f32_e32 v165, v165
	v_pk_add_f32 v[162:163], v[162:163], 1.0 op_sel_hi:[1,0]
	v_rcp_f32_e32 v160, v160
	v_pk_mul_f32 v[30:31], v[30:31], v[158:159]
	v_rcp_f32_e32 v161, v161
	v_pk_mul_f32 v[28:29], v[28:29], v[20:21]
	v_cvt_pk_bf16_f32 v185, v42, v43
	global_store_dwordx4 v[154:155], v[182:185], off
	v_exp_f32_e32 v166, v166
	v_pk_mul_f32 v[156:157], v[8:9], s[100:101] op_sel_hi:[1,0]
	v_exp_f32_e32 v167, v167
	v_pk_add_f32 v[164:165], v[164:165], 1.0 op_sel_hi:[1,0]
	v_rcp_f32_e32 v162, v162
	v_pk_mul_f32 v[24:25], v[24:25], v[160:161]
	v_rcp_f32_e32 v163, v163
	v_pk_mul_f32 v[30:31], v[30:31], v[22:23]
	v_cvt_pk_bf16_f32 v178, v28, v29
	v_add_u32_e32 v168, 0xdc000, v152
	v_exp_f32_e32 v156, v156
	v_pk_mul_f32 v[158:159], v[10:11], s[100:101] op_sel_hi:[1,0]
	v_exp_f32_e32 v157, v157
	v_pk_add_f32 v[166:167], v[166:167], 1.0 op_sel_hi:[1,0]
	v_rcp_f32_e32 v164, v164
	v_pk_mul_f32 v[26:27], v[26:27], v[162:163]
	v_rcp_f32_e32 v165, v165
	v_pk_mul_f32 v[24:25], v[24:25], v[16:17]
	v_cvt_pk_bf16_f32 v179, v30, v31
	v_exp_f32_e32 v158, v158
	v_pk_add_f32 v[156:157], v[156:157], 1.0 op_sel_hi:[1,0]
	v_exp_f32_e32 v159, v159
	v_pk_mul_f32 v[12:13], v[12:13], v[164:165]
	v_rcp_f32_e32 v166, v166
	v_pk_mul_f32 v[26:27], v[26:27], v[18:19]
	v_rcp_f32_e32 v167, v167
	v_cvt_pk_bf16_f32 v180, v24, v25
	v_lshl_add_u64 v[154:155], v[168:169], 1, s[64:65]
	v_rcp_f32_e32 v156, v156
	v_pk_add_f32 v[158:159], v[158:159], 1.0 op_sel_hi:[1,0]
	v_rcp_f32_e32 v157, v157
	v_pk_mul_f32 v[14:15], v[14:15], v[166:167]
	v_pk_mul_f32 v[12:13], v[12:13], v[4:5]
	v_cvt_pk_bf16_f32 v181, v26, v27
	global_store_dwordx4 v[154:155], v[178:181], off
	v_rcp_f32_e32 v158, v158
	v_pk_mul_f32 v[8:9], v[8:9], v[156:157]
	v_rcp_f32_e32 v159, v159
	v_pk_mul_f32 v[14:15], v[14:15], v[6:7]
	v_cvt_pk_bf16_f32 v182, v12, v13
	v_add_u32_e32 v168, 0xf2000, v152
	v_pk_mul_f32 v[10:11], v[10:11], v[158:159]
	v_pk_mul_f32 v[8:9], v[8:9], v[0:1]
	v_cvt_pk_bf16_f32 v183, v14, v15
	v_pk_mul_f32 v[10:11], v[10:11], v[2:3]
	v_cvt_pk_bf16_f32 v184, v8, v9
	v_lshl_add_u64 v[154:155], v[168:169], 1, s[64:65]
	v_cvt_pk_bf16_f32 v185, v10, v11
	global_store_dwordx4 v[154:155], v[182:185], off
	s_cbranch_vccnz .LBB0_979
	s_andn2_b64 vcc, exec, s[4:5]
	s_cbranch_vccnz .LBB0_978
	s_barrier
	s_branch .LBB0_978
